# attention loop static s_setprio 1 on the older half (waves 0-3) instead of the younger half
# baseline (speedup 1.0000x reference)
; __device__ __forceinline__ void attn_block(LAS unsigned char* lds, const Ptrs& P, int b, int h, int qb, float negMb, float lam, int tid, int wid, int lane) {
;     const int comp = wid & 1, quarter = wid >> 1, l31 = lane & 31, hh = lane >> 5;
;     const int NT = 2 * qb + 2;
;     const size_t tok0 = (size_t)b * SEQ;
;     const int qpos = qb * 128 + quarter * 32 + l31;
;     bf16x8 qf[8];
;     { const bf16* qp = P.Q + (tok0 + qpos) * 1024 + h * 256 + comp * 128 + hh * 8;
; #pragma unroll
;       for (int ks = 0; ks < 8; ++ks) qf[ks] = *(const bf16x8*)(qp + ks * 16); }
;     const unsigned ldsw = (unsigned)wid * 4096u;
;     const unsigned lds0 = (unsigned)__builtin_amdgcn_readfirstlane((int)(unsigned)(uintptr_t)lds);
;     unsigned kb0, kx16, vb0, vy16;
;     { int ln_ = lane; asm volatile("" : "+v"(ln_));
;       kb0 = (unsigned)(((16 * (wid & 3) + (ln_ >> 4)) * 1024 + h * 256 + (wid >> 2) * 128) * 2); kx16 = (unsigned)(((ln_ & 15) ^ (ln_ >> 4)) << 4);
;       vb0 = (unsigned)(((h * 256 + 32 * wid + (ln_ >> 3)) * M_TOK) * 2); vy16 = (unsigned)(((ln_ & 7) ^ (ln_ >> 4)) << 4);
;       asm volatile("" : "+v"(kb0), "+v"(kx16), "+v"(vb0), "+v"(vy16)); }
;     ...
;     f32x16 o[8];
; #pragma unroll
;     for (int e = 0; e < 8; ++e)
; #pragma unroll
;         for (int r = 0; r < 16; ++r) o[e][r] = 0.f;
.LBB0_413:
	s_xor_b64 s[40:41], s[0:1], -1
	s_and_b64 s[0:1], s[0:1], exec
	s_cselect_b32 s2, s78, s77
	s_lshl_b32 s80, s2, 7
	s_add_i32 s80, s80, s50
	v_or_b32_e32 v194, s80, v203
	v_lshl_add_u64 v[18:19], s[20:21], 0, v[194:195]
	v_lshlrev_b64 v[18:19], 11, v[18:19]
	v_lshl_add_u64 v[18:19], v[198:199], 0, v[18:19]
	flat_load_dwordx4 v[190:193], v[18:19]
	flat_load_dwordx4 v[186:189], v[18:19] offset:32
	flat_load_dwordx4 v[182:185], v[18:19] offset:64
	flat_load_dwordx4 v[178:181], v[18:19] offset:96
	flat_load_dwordx4 v[174:177], v[18:19] offset:128
	flat_load_dwordx4 v[166:169], v[18:19] offset:160
	flat_load_dwordx4 v[170:173], v[18:19] offset:192
	flat_load_dwordx4 v[162:165], v[18:19] offset:224
	v_mov_b32_e32 v51, v1
	s_lshl_b32 s82, s2, 17
	v_ashrrev_i32_e32 v52, 4, v51
	v_lshrrev_b32_e32 v53, 3, v51
	v_add_u32_e32 v54, s51, v52
	v_bitop3_b32 v55, v51, v52, 15 bitop3:0x6c
	v_bitop3_b32 v51, v51, v52, 7 bitop3:0x6c
	v_add_lshl_u32 v53, s79, v53, 16
	v_lshl_add_u32 v52, v54, 11, s4
	v_lshlrev_b32_e32 v54, 4, v55
	v_lshlrev_b32_e32 v51, 4, v51
	s_waitcnt vmcnt(0)
	v_mov_b32_e32 v194, 0
	v_add_u32_e32 v206, v52, v54
	v_xor_b32_e32 v55, 64, v54
	v_xor_b32_e32 v56, 0x80, v54
	v_add3_u32 v208, v52, v55, s71
	v_xor_b32_e32 v54, 0xc0, v54
	v_add3_u32 v209, v52, v56, s72
	v_add3_u32 v210, v52, v54, s73
	v_add_u32_e32 v207, v53, v51
	v_xad_u32 v51, v51, 64, v53
	v_add_u32_e32 v211, 0x80000, v51
	v_add_u32_e32 v212, 0x100000, v207
	v_add_u32_e32 v213, 0x180000, v51
	s_mov_b32 s81, 0
	s_mov_b64 s[0:1], s[38:39]
	s_mov_b64 s[42:43], s[36:37]
	v_mov_b32_e32 v18, 0
	v_mov_b32_e32 v34, 0
	v_mov_b32_e32 v50, 0
	v_mov_b32_e32 v19, v194
	v_mov_b32_e32 v20, v194
	v_mov_b32_e32 v21, v194
	v_mov_b32_e32 v22, v194
	v_mov_b32_e32 v23, v194
	v_mov_b32_e32 v24, v194
	v_mov_b32_e32 v25, v194
	v_mov_b32_e32 v26, v194
	v_mov_b32_e32 v27, v194
	v_mov_b32_e32 v28, v194
	v_mov_b32_e32 v29, v194
	v_mov_b32_e32 v30, v194
	v_mov_b32_e32 v31, v194
	v_mov_b32_e32 v32, v194
	v_mov_b32_e32 v33, v194
	v_mov_b32_e32 v35, v194
	v_mov_b32_e32 v36, v194
	v_mov_b32_e32 v37, v194
	v_mov_b32_e32 v38, v194
	v_mov_b32_e32 v39, v194
	v_mov_b32_e32 v40, v194
	v_mov_b32_e32 v41, v194
	v_mov_b32_e32 v42, v194
	v_mov_b32_e32 v43, v194
	v_mov_b32_e32 v44, v194
	v_mov_b32_e32 v45, v194
	v_mov_b32_e32 v46, v194
	v_mov_b32_e32 v47, v194
	v_mov_b32_e32 v48, v194
	v_mov_b32_e32 v49, v194
	s_bitset1_b32 s82, 16
	v_mov_b32_e32 v51, v194
	v_mov_b32_e32 v52, v194
	v_mov_b32_e32 v53, v194
	v_mov_b32_e32 v54, v194
	v_mov_b32_e32 v55, v194
	v_mov_b32_e32 v56, v194
	v_mov_b32_e32 v57, v194
	v_mov_b32_e32 v58, v194
	s_waitcnt vmcnt(0) lgkmcnt(0)
; #define LAS __attribute__((address_space(3)))
; #define LDS_WAIT() asm volatile("s_waitcnt lgkmcnt(0)" ::: "memory")
; __device__ __forceinline__ int pi32(int i) { return (i & ~12) | ((i & 4) << 1) | ((i & 8) >> 1); }
; #define ATT_WAIT_V(n) asm volatile("s_waitcnt vmcnt(" #n ")" ::: "memory")
; #define ATT_BAR() do { asm volatile("" ::: "memory"); __builtin_amdgcn_s_barrier(); asm volatile("" ::: "memory"); } while (0)
; __device__ __forceinline__ void attn_block(LAS unsigned char* lds, const Ptrs& P, int b, int h, int qb, float negMb, float lam, int tid, int wid, int lane) {
;     ...
;     f32x16 o[8];
; #pragma unroll
;     for (int e = 0; e < 8; ++e)
; #pragma unroll
;         for (int r = 0; r < 16; ++r) o[e][r] = 0.f;
;     float lsum = 0.f;
;     ATT_WAIT_V(0);
; #pragma unroll
;     for (int ks = 0; ks < 8; ++ks) asm volatile("" : "+v"(qf[ks]));
;     ATT_DMA(0, 0);
;     const bool early = wid < 4;
;     for (int t = 0; t < NT; ++t) {
;         ATT_WAIT_V(0);
;         LDS_WAIT();
;         ATT_BAR();
;         const bool more = t + 1 < NT;
;         if (more && early) ATT_DMA(t + 1, (t + 1) & 1);
;         const bool active = (quarter >= 2) || more;
;         const LAS unsigned char* base = lds + (t & 1) * BUF;
;         int ln2 = lane; asm volatile("" : "+v"(ln2));
;         const int l31b = ln2 & 31, hhb = ln2 >> 5;
;         const int krow = pi32(l31b), kx = krow & 15;
;         const int koffr = comp * 16384 + krow * 256;
;         const int vx = (l31b >> 1) & 7;
;         const int voffr = V_OFF + l31b * 128;
	s_mov_b32 s2, m0
	s_mov_b32 m0, s54
	s_nop 0
	global_load_lds_dwordx4 v206, s[24:25]
	s_mov_b32 m0, s2
	v_mov_b32_e32 v59, v194
	s_mov_b32 s2, m0
	s_mov_b32 m0, s55
	s_nop 0
	global_load_lds_dwordx4 v208, s[24:25]
	s_mov_b32 m0, s2
	v_mov_b32_e32 v60, v194
	s_mov_b32 s2, m0
	s_mov_b32 m0, s56
	s_nop 0
	global_load_lds_dwordx4 v209, s[24:25]
	s_mov_b32 m0, s2
	v_mov_b32_e32 v61, v194
	s_mov_b32 s2, m0
	s_mov_b32 m0, s57
	s_nop 0
	global_load_lds_dwordx4 v210, s[24:25]
	s_mov_b32 m0, s2
	v_mov_b32_e32 v62, v194
	s_mov_b32 s2, m0
	s_mov_b32 m0, s61
	s_nop 0
	global_load_lds_dwordx4 v207, s[26:27]
	s_mov_b32 m0, s2
	v_mov_b32_e32 v63, v194
	s_mov_b32 s2, m0
	s_mov_b32 m0, s62
	s_nop 0
	global_load_lds_dwordx4 v211, s[26:27]
	s_mov_b32 m0, s2
	v_mov_b32_e32 v64, v194
	s_mov_b32 s2, m0
	s_mov_b32 m0, s63
	s_nop 0
	global_load_lds_dwordx4 v212, s[26:27]
	s_mov_b32 m0, s2
	v_mov_b32_e32 v65, v194
	s_mov_b32 s2, m0
	s_mov_b32 m0, s64
	s_nop 0
	global_load_lds_dwordx4 v213, s[26:27]
	s_mov_b32 m0, s2
	v_mov_b32_e32 v66, 0
	v_mov_b32_e32 v67, v194
	v_mov_b32_e32 v68, v194
	v_mov_b32_e32 v69, v194
	v_mov_b32_e32 v70, v194
	v_mov_b32_e32 v71, v194
	v_mov_b32_e32 v72, v194
	v_mov_b32_e32 v73, v194
	v_mov_b32_e32 v74, v194
	v_mov_b32_e32 v75, v194
	v_mov_b32_e32 v76, v194
	v_mov_b32_e32 v77, v194
	v_mov_b32_e32 v78, v194
	v_mov_b32_e32 v79, v194
	v_mov_b32_e32 v80, v194
	v_mov_b32_e32 v81, v194
	v_mov_b32_e32 v82, 0
	v_mov_b32_e32 v83, v194
	v_mov_b32_e32 v84, v194
	v_mov_b32_e32 v85, v194
	v_mov_b32_e32 v86, v194
	v_mov_b32_e32 v87, v194
	v_mov_b32_e32 v88, v194
	v_mov_b32_e32 v89, v194
	v_mov_b32_e32 v90, v194
	v_mov_b32_e32 v91, v194
	v_mov_b32_e32 v92, v194
	v_mov_b32_e32 v93, v194
	v_mov_b32_e32 v94, v194
	v_mov_b32_e32 v95, v194
	v_mov_b32_e32 v96, v194
	v_mov_b32_e32 v97, v194
	v_mov_b32_e32 v98, 0
	v_mov_b32_e32 v99, v194
	v_mov_b32_e32 v100, v194
	v_mov_b32_e32 v101, v194
	v_mov_b32_e32 v102, v194
	v_mov_b32_e32 v103, v194
	v_mov_b32_e32 v104, v194
	v_mov_b32_e32 v105, v194
	v_mov_b32_e32 v106, v194
	v_mov_b32_e32 v107, v194
	v_mov_b32_e32 v108, v194
	v_mov_b32_e32 v109, v194
	v_mov_b32_e32 v110, v194
	v_mov_b32_e32 v111, v194
	v_mov_b32_e32 v112, v194
	v_mov_b32_e32 v113, v194
	v_mov_b32_e32 v114, 0
	v_mov_b32_e32 v115, v194
	v_mov_b32_e32 v116, v194
	v_mov_b32_e32 v117, v194
	v_mov_b32_e32 v118, v194
	v_mov_b32_e32 v119, v194
	v_mov_b32_e32 v120, v194
	v_mov_b32_e32 v121, v194
	v_mov_b32_e32 v122, v194
	v_mov_b32_e32 v123, v194
	v_mov_b32_e32 v124, v194
	v_mov_b32_e32 v125, v194
	v_mov_b32_e32 v126, v194
	v_mov_b32_e32 v127, v194
	v_mov_b32_e32 v128, v194
	v_mov_b32_e32 v129, v194
	v_mov_b32_e32 v130, 0
	v_mov_b32_e32 v131, v194
	v_mov_b32_e32 v132, v194
	v_mov_b32_e32 v133, v194
	v_mov_b32_e32 v134, v194
	v_mov_b32_e32 v135, v194
	v_mov_b32_e32 v136, v194
	v_mov_b32_e32 v137, v194
	v_mov_b32_e32 v138, v194
	v_mov_b32_e32 v139, v194
	v_mov_b32_e32 v140, v194
	v_mov_b32_e32 v141, v194
	v_mov_b32_e32 v142, v194
	v_mov_b32_e32 v143, v194
	v_mov_b32_e32 v144, v194
	v_mov_b32_e32 v145, v194
	v_lshrrev_b32_e32 v226, 5, v1
	v_and_b32_e32 v227, 19, v1
	v_lshlrev_b32_e32 v228, 1, v1
	v_and_b32_e32 v228, 8, v228
	v_lshrrev_b32_e32 v229, 1, v1
	v_and_b32_e32 v230, 4, v229
	v_or3_b32 v227, v227, v228, v230
	v_and_b32_e32 v231, 15, v227
	v_lshl_add_u32 v232, v227, 8, s65
	v_xor_b32_e32 v233, v226, v231
	v_lshl_add_u32 v214, v233, 4, v232
	v_add_u32_e32 v233, 2, v226
	v_xor_b32_e32 v233, v233, v231
	v_lshl_add_u32 v215, v233, 4, v232
	v_add_u32_e32 v233, 4, v226
	v_xor_b32_e32 v233, v233, v231
	v_lshl_add_u32 v216, v233, 4, v232
	v_add_u32_e32 v233, 6, v226
	v_xor_b32_e32 v233, v233, v231
	v_lshl_add_u32 v217, v233, 4, v232
	v_add_u32_e32 v233, 8, v226
	v_xor_b32_e32 v233, v233, v231
	v_lshl_add_u32 v218, v233, 4, v232
	v_add_u32_e32 v233, 10, v226
	v_xor_b32_e32 v233, v233, v231
	v_lshl_add_u32 v219, v233, 4, v232
	v_add_u32_e32 v233, 12, v226
	v_xor_b32_e32 v233, v233, v231
	v_lshl_add_u32 v220, v233, 4, v232
	v_add_u32_e32 v233, 14, v226
	v_xor_b32_e32 v233, v233, v231
	v_lshl_add_u32 v221, v233, 4, v232
	v_and_b32_e32 v234, 7, v229
	v_and_b32_e32 v235, 31, v1
	v_lshlrev_b32_e32 v235, 7, v235
	v_xor_b32_e32 v233, v226, v234
	v_lshl_add_u32 v222, v233, 4, v235
	v_add_u32_e32 v233, 2, v226
	v_xor_b32_e32 v233, v233, v234
	v_lshl_add_u32 v223, v233, 4, v235
	v_add_u32_e32 v233, 4, v226
	v_xor_b32_e32 v233, v233, v234
	v_lshl_add_u32 v224, v233, 4, v235
	v_add_u32_e32 v233, 6, v226
	v_xor_b32_e32 v233, v233, v234
	v_lshl_add_u32 v225, v233, 4, v235
	v_mov_b32_e32 v254, 0
	v_mov_b32_e32 v255, 0
	s_and_b64 vcc, exec, s[12:13]
	s_cbranch_vccnz .Lat_noprio
	s_setprio 1
